# GEMM K-loops: dropped the back-to-back s_setprio 0/s_setprio 1 pair between the two 16-MFMA halves of each compute segment (16 sites)
# speedup vs baseline: 1.0157x; 1.0027x over previous
.LBB0_176:
	s_add_u32 s2, s14, 0xfffc0080
	s_addc_u32 s3, s15, -1
	s_add_i32 s47, 0, 0x10000
	s_cmp_eq_u32 s46, 12
	s_cselect_b32 s25, s7, s3
	s_cselect_b32 s24, s11, s2
	v_add_u32_e32 v0, s47, v155
	s_cselect_b32 s3, s13, s33
	s_cselect_b32 s2, s29, s31
	s_add_i32 s54, 0, 0x14000
	ds_read_b128 v[50:53], v0
	ds_read_b128 v[54:57], v0 offset:1024
	ds_read_b128 v[58:61], v0 offset:2048
	ds_read_b128 v[62:65], v0 offset:3072
	v_add_u32_e32 v0, s54, v155
	ds_read_b128 v[176:179], v0
	ds_read_b128 v[188:191], v0 offset:1024
	ds_read_b128 v[192:195], v0 offset:2048
	ds_read_b128 v[196:199], v0 offset:3072
	v_lshl_add_u64 v[180:181], s[14:15], 0, v[170:171]
	s_add_i32 m0, s90, 0xc000
	ds_read_b128 v[200:203], v186
	ds_read_b128 v[204:207], v186 offset:1024
	ds_read_b128 v[226:229], v186 offset:2048
	ds_read_b128 v[230:233], v186 offset:3072
	ds_read_b128 v[234:237], v186 offset:4096
	ds_read_b128 v[238:241], v186 offset:5120
	ds_read_b128 v[242:245], v186 offset:6144
	ds_read_b128 v[246:249], v186 offset:7168
	global_load_lds_dwordx4 v[180:181], off
	v_lshl_add_u64 v[180:181], s[14:15], 0, v[172:173]
	s_add_i32 m0, s90, 0xe000
	s_nop 0
	global_load_lds_dwordx4 v[180:181], off
	s_waitcnt vmcnt(8)
	s_waitcnt lgkmcnt(0)
	s_barrier
	s_setprio 1
	s_waitcnt lgkmcnt(0)
	v_mfma_f32_16x16x32_bf16 v[142:145], v[50:53], v[200:203], v[142:145]
	v_mfma_f32_16x16x32_bf16 v[138:141], v[58:61], v[200:203], v[138:141]
	v_mfma_f32_16x16x32_bf16 v[126:129], v[50:53], v[226:229], v[126:129]
	v_mfma_f32_16x16x32_bf16 v[122:125], v[58:61], v[226:229], v[122:125]
	v_mfma_f32_16x16x32_bf16 v[110:113], v[50:53], v[234:237], v[110:113]
	v_mfma_f32_16x16x32_bf16 v[106:109], v[58:61], v[234:237], v[106:109]
	v_mfma_f32_16x16x32_bf16 v[94:97], v[50:53], v[242:245], v[94:97]
	v_mfma_f32_16x16x32_bf16 v[90:93], v[58:61], v[242:245], v[90:93]
	v_mfma_f32_16x16x32_bf16 v[142:145], v[54:57], v[204:207], v[142:145]
	v_mfma_f32_16x16x32_bf16 v[138:141], v[62:65], v[204:207], v[138:141]
	v_mfma_f32_16x16x32_bf16 v[126:129], v[54:57], v[230:233], v[126:129]
	v_mfma_f32_16x16x32_bf16 v[122:125], v[62:65], v[230:233], v[122:125]
	v_mfma_f32_16x16x32_bf16 v[110:113], v[54:57], v[238:241], v[110:113]
	v_mfma_f32_16x16x32_bf16 v[106:109], v[62:65], v[238:241], v[106:109]
	v_mfma_f32_16x16x32_bf16 v[94:97], v[54:57], v[246:249], v[94:97]
	v_mfma_f32_16x16x32_bf16 v[90:93], v[62:65], v[246:249], v[90:93]
	v_mfma_f32_16x16x32_bf16 v[134:137], v[176:179], v[200:203], v[134:137]
	v_mfma_f32_16x16x32_bf16 v[130:133], v[192:195], v[200:203], v[130:133]
	v_mfma_f32_16x16x32_bf16 v[118:121], v[176:179], v[226:229], v[118:121]
	v_mfma_f32_16x16x32_bf16 v[114:117], v[192:195], v[226:229], v[114:117]
	v_mfma_f32_16x16x32_bf16 v[102:105], v[176:179], v[234:237], v[102:105]
	v_mfma_f32_16x16x32_bf16 v[98:101], v[192:195], v[234:237], v[98:101]
	v_mfma_f32_16x16x32_bf16 v[86:89], v[176:179], v[242:245], v[86:89]
	v_mfma_f32_16x16x32_bf16 v[82:85], v[192:195], v[242:245], v[82:85]
	v_mfma_f32_16x16x32_bf16 v[134:137], v[188:191], v[204:207], v[134:137]
	v_mfma_f32_16x16x32_bf16 v[130:133], v[196:199], v[204:207], v[130:133]
	v_mfma_f32_16x16x32_bf16 v[118:121], v[188:191], v[230:233], v[118:121]
	v_mfma_f32_16x16x32_bf16 v[114:117], v[196:199], v[230:233], v[114:117]
	v_mfma_f32_16x16x32_bf16 v[102:105], v[188:191], v[238:241], v[102:105]
	v_mfma_f32_16x16x32_bf16 v[98:101], v[196:199], v[238:241], v[98:101]
	v_mfma_f32_16x16x32_bf16 v[86:89], v[188:191], v[246:249], v[86:89]
	v_mfma_f32_16x16x32_bf16 v[82:85], v[196:199], v[246:249], v[82:85]
	s_setprio 0
	s_barrier
	s_add_i32 s47, s47, s42
	v_lshl_add_u64 v[180:181], s[2:3], 0, v[146:147]
	s_mov_b32 m0, s47
	ds_read_b128 v[200:203], v186 offset:16384
	ds_read_b128 v[204:207], v186 offset:17408
	ds_read_b128 v[226:229], v186 offset:18432
	ds_read_b128 v[230:233], v186 offset:19456
	ds_read_b128 v[234:237], v186 offset:20480
	ds_read_b128 v[238:241], v186 offset:21504
	ds_read_b128 v[242:245], v186 offset:22528
	ds_read_b128 v[246:249], v186 offset:23552
	global_load_lds_dwordx4 v[180:181], off
	s_add_i32 m0, s47, 0x2000
	s_add_u32 s58, s2, 0x40000
	v_lshl_add_u64 v[222:223], s[2:3], 0, v[148:149]
	s_addc_u32 s59, s3, 0
	s_add_i32 s47, s54, s42
	global_load_lds_dwordx4 v[222:223], off
	v_lshl_add_u64 v[224:225], s[58:59], 0, v[146:147]
	s_mov_b32 m0, s47
	v_lshl_add_u64 v[250:251], s[24:25], 0, v[148:149]
	global_load_lds_dwordx4 v[224:225], off
	v_lshl_add_u64 v[224:225], s[58:59], 0, v[148:149]
	s_add_i32 m0, s47, 0x2000
	s_nop 0
	global_load_lds_dwordx4 v[224:225], off
	v_lshl_add_u64 v[224:225], s[24:25], 0, v[146:147]
	s_mov_b32 m0, s90
	s_nop 0
	global_load_lds_dwordx4 v[224:225], off
	s_mov_b32 m0, s91
	s_nop 0
	global_load_lds_dwordx4 v[250:251], off
	s_waitcnt vmcnt(8)
	s_waitcnt lgkmcnt(0)
	s_barrier
	s_setprio 1
	s_waitcnt lgkmcnt(0)
	v_mfma_f32_16x16x32_bf16 v[78:81], v[50:53], v[200:203], v[78:81]
	v_mfma_f32_16x16x32_bf16 v[74:77], v[58:61], v[200:203], v[74:77]
	v_mfma_f32_16x16x32_bf16 v[46:49], v[50:53], v[226:229], v[46:49]
	v_mfma_f32_16x16x32_bf16 v[42:45], v[58:61], v[226:229], v[42:45]
	v_mfma_f32_16x16x32_bf16 v[30:33], v[50:53], v[234:237], v[30:33]
	v_mfma_f32_16x16x32_bf16 v[26:29], v[58:61], v[234:237], v[26:29]
	v_mfma_f32_16x16x32_bf16 v[14:17], v[50:53], v[242:245], v[14:17]
	v_mfma_f32_16x16x32_bf16 v[10:13], v[58:61], v[242:245], v[10:13]
	v_mfma_f32_16x16x32_bf16 v[78:81], v[54:57], v[204:207], v[78:81]
	v_mfma_f32_16x16x32_bf16 v[74:77], v[62:65], v[204:207], v[74:77]
	v_mfma_f32_16x16x32_bf16 v[46:49], v[54:57], v[230:233], v[46:49]
	v_mfma_f32_16x16x32_bf16 v[42:45], v[62:65], v[230:233], v[42:45]
	v_mfma_f32_16x16x32_bf16 v[30:33], v[54:57], v[238:241], v[30:33]
	v_mfma_f32_16x16x32_bf16 v[26:29], v[62:65], v[238:241], v[26:29]
	v_mfma_f32_16x16x32_bf16 v[14:17], v[54:57], v[246:249], v[14:17]
	v_mfma_f32_16x16x32_bf16 v[10:13], v[62:65], v[246:249], v[10:13]
	v_mfma_f32_16x16x32_bf16 v[38:41], v[176:179], v[226:229], v[38:41]
	v_mfma_f32_16x16x32_bf16 v[34:37], v[192:195], v[226:229], v[34:37]
	v_mfma_f32_16x16x32_bf16 v[22:25], v[176:179], v[234:237], v[22:25]
	v_mfma_f32_16x16x32_bf16 v[18:21], v[192:195], v[234:237], v[18:21]
	v_mfma_f32_16x16x32_bf16 v[6:9], v[176:179], v[242:245], v[6:9]
	v_mfma_f32_16x16x32_bf16 v[2:5], v[192:195], v[242:245], v[2:5]
	v_mfma_f32_16x16x32_bf16 v[50:53], v[176:179], v[200:203], v[70:73]
	v_mfma_f32_16x16x32_bf16 v[54:57], v[192:195], v[200:203], v[66:69]
	v_mfma_f32_16x16x32_bf16 v[38:41], v[188:191], v[230:233], v[38:41]
	v_mfma_f32_16x16x32_bf16 v[34:37], v[196:199], v[230:233], v[34:37]
	v_mfma_f32_16x16x32_bf16 v[22:25], v[188:191], v[238:241], v[22:25]
	v_mfma_f32_16x16x32_bf16 v[18:21], v[196:199], v[238:241], v[18:21]
	v_mfma_f32_16x16x32_bf16 v[6:9], v[188:191], v[246:249], v[6:9]
	v_mfma_f32_16x16x32_bf16 v[2:5], v[196:199], v[246:249], v[2:5]
	v_mfma_f32_16x16x32_bf16 v[50:53], v[188:191], v[204:207], v[50:53]
	v_mfma_f32_16x16x32_bf16 v[54:57], v[196:199], v[204:207], v[54:57]
	s_setprio 0
	s_barrier
	s_add_i32 s47, 0, 0x18000
	v_add_u32_e32 v0, s47, v155
	s_add_i32 s54, 0, 0x1c000
	ds_read_b128 v[58:61], v0
	ds_read_b128 v[62:65], v0 offset:1024
	ds_read_b128 v[66:69], v0 offset:2048
	ds_read_b128 v[70:73], v0 offset:3072
	v_add_u32_e32 v0, s54, v155
	ds_read_b128 v[176:179], v0
	ds_read_b128 v[188:191], v0 offset:1024
	ds_read_b128 v[192:195], v0 offset:2048
	ds_read_b128 v[196:199], v0 offset:3072
	s_add_u32 s24, s24, 0x40000
	s_addc_u32 s25, s25, 0
	s_mov_b32 m0, s74
	v_lshl_add_u64 v[218:219], s[24:25], 0, v[146:147]
	ds_read_b128 v[200:203], v186 offset:32768
	ds_read_b128 v[204:207], v186 offset:33792
	ds_read_b128 v[226:229], v186 offset:34816
	ds_read_b128 v[230:233], v186 offset:35840
	ds_read_b128 v[234:237], v186 offset:36864
	ds_read_b128 v[238:241], v186 offset:37888
	ds_read_b128 v[242:245], v186 offset:38912
	ds_read_b128 v[246:249], v186 offset:39936
	global_load_lds_dwordx4 v[218:219], off
	v_lshl_add_u64 v[218:219], s[24:25], 0, v[148:149]
	s_mov_b32 m0, s75
	s_nop 0
	global_load_lds_dwordx4 v[218:219], off
	s_waitcnt vmcnt(8)
	s_waitcnt lgkmcnt(0)
	s_barrier
	s_setprio 1
	s_waitcnt lgkmcnt(0)
	v_mfma_f32_16x16x32_bf16 v[142:145], v[58:61], v[200:203], v[142:145]
	v_mfma_f32_16x16x32_bf16 v[138:141], v[66:69], v[200:203], v[138:141]
	v_mfma_f32_16x16x32_bf16 v[126:129], v[58:61], v[226:229], v[126:129]
	v_mfma_f32_16x16x32_bf16 v[122:125], v[66:69], v[226:229], v[122:125]
	v_mfma_f32_16x16x32_bf16 v[110:113], v[58:61], v[234:237], v[110:113]
	v_mfma_f32_16x16x32_bf16 v[106:109], v[66:69], v[234:237], v[106:109]
	v_mfma_f32_16x16x32_bf16 v[94:97], v[58:61], v[242:245], v[94:97]
	v_mfma_f32_16x16x32_bf16 v[90:93], v[66:69], v[242:245], v[90:93]
	v_mfma_f32_16x16x32_bf16 v[142:145], v[62:65], v[204:207], v[142:145]
	v_mfma_f32_16x16x32_bf16 v[138:141], v[70:73], v[204:207], v[138:141]
	v_mfma_f32_16x16x32_bf16 v[126:129], v[62:65], v[230:233], v[126:129]
	v_mfma_f32_16x16x32_bf16 v[122:125], v[70:73], v[230:233], v[122:125]
	v_mfma_f32_16x16x32_bf16 v[110:113], v[62:65], v[238:241], v[110:113]
	v_mfma_f32_16x16x32_bf16 v[106:109], v[70:73], v[238:241], v[106:109]
	v_mfma_f32_16x16x32_bf16 v[94:97], v[62:65], v[246:249], v[94:97]
	v_mfma_f32_16x16x32_bf16 v[90:93], v[70:73], v[246:249], v[90:93]
	v_mfma_f32_16x16x32_bf16 v[134:137], v[176:179], v[200:203], v[134:137]
	v_mfma_f32_16x16x32_bf16 v[130:133], v[192:195], v[200:203], v[130:133]
	v_mfma_f32_16x16x32_bf16 v[118:121], v[176:179], v[226:229], v[118:121]
	v_mfma_f32_16x16x32_bf16 v[114:117], v[192:195], v[226:229], v[114:117]
	v_mfma_f32_16x16x32_bf16 v[102:105], v[176:179], v[234:237], v[102:105]
	v_mfma_f32_16x16x32_bf16 v[98:101], v[192:195], v[234:237], v[98:101]
	v_mfma_f32_16x16x32_bf16 v[86:89], v[176:179], v[242:245], v[86:89]
	v_mfma_f32_16x16x32_bf16 v[82:85], v[192:195], v[242:245], v[82:85]
	v_mfma_f32_16x16x32_bf16 v[134:137], v[188:191], v[204:207], v[134:137]
	v_mfma_f32_16x16x32_bf16 v[130:133], v[196:199], v[204:207], v[130:133]
	v_mfma_f32_16x16x32_bf16 v[118:121], v[188:191], v[230:233], v[118:121]
	v_mfma_f32_16x16x32_bf16 v[114:117], v[196:199], v[230:233], v[114:117]
	v_mfma_f32_16x16x32_bf16 v[102:105], v[188:191], v[238:241], v[102:105]
	v_mfma_f32_16x16x32_bf16 v[98:101], v[196:199], v[238:241], v[98:101]
	v_mfma_f32_16x16x32_bf16 v[86:89], v[188:191], v[246:249], v[86:89]
	v_mfma_f32_16x16x32_bf16 v[82:85], v[196:199], v[246:249], v[82:85]
	s_setprio 0
	s_barrier
	s_add_i32 s24, s47, s42
	v_lshl_add_u64 v[180:181], v[180:181], 0, s[44:45]
	s_mov_b32 m0, s24
	ds_read_b128 v[200:203], v186 offset:49152
	ds_read_b128 v[204:207], v186 offset:50176
	ds_read_b128 v[226:229], v186 offset:51200
	ds_read_b128 v[230:233], v186 offset:52224
	ds_read_b128 v[234:237], v186 offset:53248
	ds_read_b128 v[238:241], v186 offset:54272
	ds_read_b128 v[242:245], v186 offset:55296
	ds_read_b128 v[246:249], v186 offset:56320
	global_load_lds_dwordx4 v[180:181], off
	s_add_i32 m0, s24, 0x2000
	s_add_u32 s2, s2, 0x40080
	v_lshl_add_u64 v[180:181], v[222:223], 0, s[44:45]
	s_addc_u32 s3, s3, 0
	s_add_i32 s24, s54, s42
	global_load_lds_dwordx4 v[180:181], off
	v_lshl_add_u64 v[180:181], s[2:3], 0, v[146:147]
	s_mov_b32 m0, s24
	s_nop 0
	global_load_lds_dwordx4 v[180:181], off
	v_lshl_add_u64 v[180:181], s[2:3], 0, v[148:149]
	s_add_i32 m0, s24, 0x2000
	s_nop 0
	global_load_lds_dwordx4 v[180:181], off
	v_lshl_add_u64 v[180:181], v[224:225], 0, s[44:45]
	s_mov_b32 m0, s20
	s_nop 0
	global_load_lds_dwordx4 v[180:181], off
	v_lshl_add_u64 v[180:181], v[250:251], 0, s[44:45]
	s_mov_b32 m0, s21
	s_nop 0
	global_load_lds_dwordx4 v[180:181], off
	s_waitcnt vmcnt(8)
	s_waitcnt lgkmcnt(0)
	s_barrier
	s_setprio 1
	s_waitcnt lgkmcnt(0)
	v_mfma_f32_16x16x32_bf16 v[78:81], v[58:61], v[200:203], v[78:81]
	v_mfma_f32_16x16x32_bf16 v[74:77], v[66:69], v[200:203], v[74:77]
	v_mfma_f32_16x16x32_bf16 v[46:49], v[58:61], v[226:229], v[46:49]
	v_mfma_f32_16x16x32_bf16 v[42:45], v[66:69], v[226:229], v[42:45]
	v_mfma_f32_16x16x32_bf16 v[30:33], v[58:61], v[234:237], v[30:33]
	v_mfma_f32_16x16x32_bf16 v[26:29], v[66:69], v[234:237], v[26:29]
	v_mfma_f32_16x16x32_bf16 v[14:17], v[58:61], v[242:245], v[14:17]
	v_mfma_f32_16x16x32_bf16 v[10:13], v[66:69], v[242:245], v[10:13]
	v_mfma_f32_16x16x32_bf16 v[78:81], v[62:65], v[204:207], v[78:81]
	v_mfma_f32_16x16x32_bf16 v[74:77], v[70:73], v[204:207], v[74:77]
	v_mfma_f32_16x16x32_bf16 v[46:49], v[62:65], v[230:233], v[46:49]
	v_mfma_f32_16x16x32_bf16 v[42:45], v[70:73], v[230:233], v[42:45]
	v_mfma_f32_16x16x32_bf16 v[30:33], v[62:65], v[238:241], v[30:33]
	v_mfma_f32_16x16x32_bf16 v[26:29], v[70:73], v[238:241], v[26:29]
	v_mfma_f32_16x16x32_bf16 v[14:17], v[62:65], v[246:249], v[14:17]
	v_mfma_f32_16x16x32_bf16 v[10:13], v[70:73], v[246:249], v[10:13]
	v_mfma_f32_16x16x32_bf16 v[50:53], v[176:179], v[200:203], v[50:53]
	v_mfma_f32_16x16x32_bf16 v[70:73], v[188:191], v[204:207], v[50:53]
	v_mfma_f32_16x16x32_bf16 v[50:53], v[192:195], v[200:203], v[54:57]
	v_mfma_f32_16x16x32_bf16 v[38:41], v[176:179], v[226:229], v[38:41]
	v_mfma_f32_16x16x32_bf16 v[34:37], v[192:195], v[226:229], v[34:37]
	v_mfma_f32_16x16x32_bf16 v[22:25], v[176:179], v[234:237], v[22:25]
	v_mfma_f32_16x16x32_bf16 v[18:21], v[192:195], v[234:237], v[18:21]
	v_mfma_f32_16x16x32_bf16 v[6:9], v[176:179], v[242:245], v[6:9]
	v_mfma_f32_16x16x32_bf16 v[2:5], v[192:195], v[242:245], v[2:5]
	v_mfma_f32_16x16x32_bf16 v[66:69], v[196:199], v[204:207], v[50:53]
	v_mfma_f32_16x16x32_bf16 v[38:41], v[188:191], v[230:233], v[38:41]
	v_mfma_f32_16x16x32_bf16 v[34:37], v[196:199], v[230:233], v[34:37]
	v_mfma_f32_16x16x32_bf16 v[22:25], v[188:191], v[238:241], v[22:25]
	v_mfma_f32_16x16x32_bf16 v[18:21], v[196:199], v[238:241], v[18:21]
	v_mfma_f32_16x16x32_bf16 v[6:9], v[188:191], v[246:249], v[6:9]
	v_mfma_f32_16x16x32_bf16 v[2:5], v[196:199], v[246:249], v[2:5]
	s_setprio 0
	s_barrier
	s_add_i32 s46, s46, 2
	s_add_u32 s14, s14, 0x100
	s_addc_u32 s15, s15, 0
	s_add_u32 s31, s31, 0x100
	s_addc_u32 s33, s33, 0
	s_cmp_gt_u32 s46, 13
	s_cbranch_scc0 .LBB0_176
	s_and_b64 vcc, exec, s[22:23]
	s_cbranch_vccz .LBB0_179
	s_barrier

.LBB0_650:
	s_add_u32 s2, s4, 0x100
	s_addc_u32 s3, s5, 0
	s_add_i32 s49, 0, 0x10000
	s_cmp_eq_u32 s48, 12
	s_cselect_b32 s29, s17, s3
	s_cselect_b32 s28, s25, s2
	v_add_u32_e32 v0, s49, v135
	s_cselect_b32 s27, s15, s47
	s_cselect_b32 s26, s42, s46
	s_add_i32 s50, 0, 0x14000
	ds_read_b128 v[146:149], v0
	ds_read_b128 v[150:153], v0 offset:1024
	ds_read_b128 v[154:157], v0 offset:2048
	ds_read_b128 v[158:161], v0 offset:3072
	v_add_u32_e32 v0, s50, v135
	ds_read_b128 v[162:165], v0
	ds_read_b128 v[166:169], v0 offset:1024
	ds_read_b128 v[170:173], v0 offset:2048
	ds_read_b128 v[174:177], v0 offset:3072
	v_lshl_add_u64 v[142:143], s[4:5], 0, v[138:139]
	s_add_i32 m0, s23, 0xc000
	ds_read_b128 v[178:181], v144
	ds_read_b128 v[182:185], v144 offset:1024
	ds_read_b128 v[186:189], v144 offset:2048
	ds_read_b128 v[190:193], v144 offset:3072
	ds_read_b128 v[194:197], v144 offset:4096
	ds_read_b128 v[198:201], v144 offset:5120
	ds_read_b128 v[202:205], v144 offset:6144
	ds_read_b128 v[222:225], v144 offset:7168
	global_load_lds_dwordx4 v[142:143], off
	v_lshl_add_u64 v[142:143], s[4:5], 0, v[140:141]
	s_add_i32 m0, s23, 0xe000
	s_nop 0
	global_load_lds_dwordx4 v[142:143], off
	s_waitcnt vmcnt(8)
	s_waitcnt lgkmcnt(0)
	s_barrier
	s_setprio 1
	s_waitcnt lgkmcnt(0)
	v_mfma_f32_16x16x32_bf16 v[126:129], v[146:149], v[178:181], v[126:129]
	v_mfma_f32_16x16x32_bf16 v[122:125], v[154:157], v[178:181], v[122:125]
	v_mfma_f32_16x16x32_bf16 v[110:113], v[146:149], v[186:189], v[110:113]
	v_mfma_f32_16x16x32_bf16 v[106:109], v[154:157], v[186:189], v[106:109]
	v_mfma_f32_16x16x32_bf16 v[94:97], v[146:149], v[194:197], v[94:97]
	v_mfma_f32_16x16x32_bf16 v[90:93], v[154:157], v[194:197], v[90:93]
	v_mfma_f32_16x16x32_bf16 v[78:81], v[146:149], v[202:205], v[78:81]
	v_mfma_f32_16x16x32_bf16 v[74:77], v[154:157], v[202:205], v[74:77]
	v_mfma_f32_16x16x32_bf16 v[126:129], v[150:153], v[182:185], v[126:129]
	v_mfma_f32_16x16x32_bf16 v[122:125], v[158:161], v[182:185], v[122:125]
	v_mfma_f32_16x16x32_bf16 v[110:113], v[150:153], v[190:193], v[110:113]
	v_mfma_f32_16x16x32_bf16 v[106:109], v[158:161], v[190:193], v[106:109]
	v_mfma_f32_16x16x32_bf16 v[94:97], v[150:153], v[198:201], v[94:97]
	v_mfma_f32_16x16x32_bf16 v[90:93], v[158:161], v[198:201], v[90:93]
	v_mfma_f32_16x16x32_bf16 v[78:81], v[150:153], v[222:225], v[78:81]
	v_mfma_f32_16x16x32_bf16 v[74:77], v[158:161], v[222:225], v[74:77]
	v_mfma_f32_16x16x32_bf16 v[118:121], v[162:165], v[178:181], v[118:121]
	v_mfma_f32_16x16x32_bf16 v[114:117], v[170:173], v[178:181], v[114:117]
	v_mfma_f32_16x16x32_bf16 v[102:105], v[162:165], v[186:189], v[102:105]
	v_mfma_f32_16x16x32_bf16 v[98:101], v[170:173], v[186:189], v[98:101]
	v_mfma_f32_16x16x32_bf16 v[86:89], v[162:165], v[194:197], v[86:89]
	v_mfma_f32_16x16x32_bf16 v[82:85], v[170:173], v[194:197], v[82:85]
	v_mfma_f32_16x16x32_bf16 v[70:73], v[162:165], v[202:205], v[70:73]
	v_mfma_f32_16x16x32_bf16 v[66:69], v[170:173], v[202:205], v[66:69]
	v_mfma_f32_16x16x32_bf16 v[118:121], v[166:169], v[182:185], v[118:121]
	v_mfma_f32_16x16x32_bf16 v[114:117], v[174:177], v[182:185], v[114:117]
	v_mfma_f32_16x16x32_bf16 v[102:105], v[166:169], v[190:193], v[102:105]
	v_mfma_f32_16x16x32_bf16 v[98:101], v[174:177], v[190:193], v[98:101]
	v_mfma_f32_16x16x32_bf16 v[86:89], v[166:169], v[198:201], v[86:89]
	v_mfma_f32_16x16x32_bf16 v[82:85], v[174:177], v[198:201], v[82:85]
	v_mfma_f32_16x16x32_bf16 v[70:73], v[166:169], v[222:225], v[70:73]
	v_mfma_f32_16x16x32_bf16 v[66:69], v[174:177], v[222:225], v[66:69]
	s_setprio 0
	s_barrier
	s_add_i32 s4, s49, s30
	v_lshl_add_u64 v[142:143], s[26:27], 0, v[130:131]
	s_mov_b32 m0, s4
	ds_read_b128 v[178:181], v144 offset:16384
	ds_read_b128 v[182:185], v144 offset:17408
	ds_read_b128 v[186:189], v144 offset:18432
	ds_read_b128 v[190:193], v144 offset:19456
	ds_read_b128 v[194:197], v144 offset:20480
	ds_read_b128 v[198:201], v144 offset:21504
	ds_read_b128 v[202:205], v144 offset:22528
	ds_read_b128 v[222:225], v144 offset:23552
	global_load_lds_dwordx4 v[142:143], off
	s_add_i32 m0, s4, 0x2000
	s_add_u32 s4, s26, 0x40000
	v_lshl_add_u64 v[206:207], s[26:27], 0, v[132:133]
	s_addc_u32 s5, s27, 0
	s_add_i32 s49, s50, s30
	global_load_lds_dwordx4 v[206:207], off
	v_lshl_add_u64 v[218:219], s[4:5], 0, v[130:131]
	s_mov_b32 m0, s49
	v_lshl_add_u64 v[226:227], s[28:29], 0, v[132:133]
	global_load_lds_dwordx4 v[218:219], off
	v_lshl_add_u64 v[218:219], s[4:5], 0, v[132:133]
	s_add_i32 m0, s49, 0x2000
	s_nop 0
	global_load_lds_dwordx4 v[218:219], off
	v_lshl_add_u64 v[218:219], s[28:29], 0, v[130:131]
	s_mov_b32 m0, s23
	s_nop 0
	global_load_lds_dwordx4 v[218:219], off
	s_mov_b32 m0, s31
	s_nop 0
	global_load_lds_dwordx4 v[226:227], off
	s_waitcnt vmcnt(8)
	s_waitcnt lgkmcnt(0)
	s_barrier
	s_setprio 1
	s_waitcnt lgkmcnt(0)
	v_mfma_f32_16x16x32_bf16 v[62:65], v[146:149], v[178:181], v[62:65]
	v_mfma_f32_16x16x32_bf16 v[58:61], v[154:157], v[178:181], v[58:61]
	v_mfma_f32_16x16x32_bf16 v[46:49], v[146:149], v[186:189], v[46:49]
	v_mfma_f32_16x16x32_bf16 v[42:45], v[154:157], v[186:189], v[42:45]
	v_mfma_f32_16x16x32_bf16 v[30:33], v[146:149], v[194:197], v[30:33]
	v_mfma_f32_16x16x32_bf16 v[26:29], v[154:157], v[194:197], v[26:29]
	v_mfma_f32_16x16x32_bf16 v[14:17], v[146:149], v[202:205], v[14:17]
	v_mfma_f32_16x16x32_bf16 v[10:13], v[154:157], v[202:205], v[10:13]
	v_mfma_f32_16x16x32_bf16 v[62:65], v[150:153], v[182:185], v[62:65]
	v_mfma_f32_16x16x32_bf16 v[58:61], v[158:161], v[182:185], v[58:61]
	v_mfma_f32_16x16x32_bf16 v[46:49], v[150:153], v[190:193], v[46:49]
	v_mfma_f32_16x16x32_bf16 v[42:45], v[158:161], v[190:193], v[42:45]
	v_mfma_f32_16x16x32_bf16 v[30:33], v[150:153], v[198:201], v[30:33]
	v_mfma_f32_16x16x32_bf16 v[26:29], v[158:161], v[198:201], v[26:29]
	v_mfma_f32_16x16x32_bf16 v[14:17], v[150:153], v[222:225], v[14:17]
	v_mfma_f32_16x16x32_bf16 v[10:13], v[158:161], v[222:225], v[10:13]
	v_mfma_f32_16x16x32_bf16 v[54:57], v[162:165], v[178:181], v[54:57]
	v_mfma_f32_16x16x32_bf16 v[50:53], v[170:173], v[178:181], v[50:53]
	v_mfma_f32_16x16x32_bf16 v[38:41], v[162:165], v[186:189], v[38:41]
	v_mfma_f32_16x16x32_bf16 v[34:37], v[170:173], v[186:189], v[34:37]
	v_mfma_f32_16x16x32_bf16 v[22:25], v[162:165], v[194:197], v[22:25]
	v_mfma_f32_16x16x32_bf16 v[18:21], v[170:173], v[194:197], v[18:21]
	v_mfma_f32_16x16x32_bf16 v[6:9], v[162:165], v[202:205], v[6:9]
	v_mfma_f32_16x16x32_bf16 v[2:5], v[170:173], v[202:205], v[2:5]
	v_mfma_f32_16x16x32_bf16 v[54:57], v[166:169], v[182:185], v[54:57]
	v_mfma_f32_16x16x32_bf16 v[50:53], v[174:177], v[182:185], v[50:53]
	v_mfma_f32_16x16x32_bf16 v[38:41], v[166:169], v[190:193], v[38:41]
	v_mfma_f32_16x16x32_bf16 v[34:37], v[174:177], v[190:193], v[34:37]
	v_mfma_f32_16x16x32_bf16 v[22:25], v[166:169], v[198:201], v[22:25]
	v_mfma_f32_16x16x32_bf16 v[18:21], v[174:177], v[198:201], v[18:21]
	v_mfma_f32_16x16x32_bf16 v[6:9], v[166:169], v[222:225], v[6:9]
	v_mfma_f32_16x16x32_bf16 v[2:5], v[174:177], v[222:225], v[2:5]
	s_setprio 0
	s_barrier
	s_add_i32 s49, 0, 0x18000
	v_add_u32_e32 v0, s49, v135
	s_add_i32 s50, 0, 0x1c000
	ds_read_b128 v[146:149], v0
	ds_read_b128 v[150:153], v0 offset:1024
	ds_read_b128 v[154:157], v0 offset:2048
	ds_read_b128 v[158:161], v0 offset:3072
	v_add_u32_e32 v0, s50, v135
	ds_read_b128 v[162:165], v0
	ds_read_b128 v[166:169], v0 offset:1024
	ds_read_b128 v[170:173], v0 offset:2048
	ds_read_b128 v[174:177], v0 offset:3072
	s_add_u32 s4, s28, 0x40000
	s_addc_u32 s5, s29, 0
	s_mov_b32 m0, s33
	v_lshl_add_u64 v[228:229], s[4:5], 0, v[130:131]
	ds_read_b128 v[178:181], v144 offset:32768
	ds_read_b128 v[182:185], v144 offset:33792
	ds_read_b128 v[186:189], v144 offset:34816
	ds_read_b128 v[190:193], v144 offset:35840
	ds_read_b128 v[194:197], v144 offset:36864
	ds_read_b128 v[198:201], v144 offset:37888
	ds_read_b128 v[202:205], v144 offset:38912
	ds_read_b128 v[222:225], v144 offset:39936
	global_load_lds_dwordx4 v[228:229], off
	v_lshl_add_u64 v[228:229], s[4:5], 0, v[132:133]
	s_mov_b32 m0, s34
	s_nop 0
	global_load_lds_dwordx4 v[228:229], off
	s_waitcnt vmcnt(8)
	s_waitcnt lgkmcnt(0)
	s_barrier
	s_setprio 1
	s_waitcnt lgkmcnt(0)
	v_mfma_f32_16x16x32_bf16 v[126:129], v[146:149], v[178:181], v[126:129]
	v_mfma_f32_16x16x32_bf16 v[122:125], v[154:157], v[178:181], v[122:125]
	v_mfma_f32_16x16x32_bf16 v[110:113], v[146:149], v[186:189], v[110:113]
	v_mfma_f32_16x16x32_bf16 v[106:109], v[154:157], v[186:189], v[106:109]
	v_mfma_f32_16x16x32_bf16 v[94:97], v[146:149], v[194:197], v[94:97]
	v_mfma_f32_16x16x32_bf16 v[90:93], v[154:157], v[194:197], v[90:93]
	v_mfma_f32_16x16x32_bf16 v[78:81], v[146:149], v[202:205], v[78:81]
	v_mfma_f32_16x16x32_bf16 v[74:77], v[154:157], v[202:205], v[74:77]
	v_mfma_f32_16x16x32_bf16 v[126:129], v[150:153], v[182:185], v[126:129]
	v_mfma_f32_16x16x32_bf16 v[122:125], v[158:161], v[182:185], v[122:125]
	v_mfma_f32_16x16x32_bf16 v[110:113], v[150:153], v[190:193], v[110:113]
	v_mfma_f32_16x16x32_bf16 v[106:109], v[158:161], v[190:193], v[106:109]
	v_mfma_f32_16x16x32_bf16 v[94:97], v[150:153], v[198:201], v[94:97]
	v_mfma_f32_16x16x32_bf16 v[90:93], v[158:161], v[198:201], v[90:93]
	v_mfma_f32_16x16x32_bf16 v[78:81], v[150:153], v[222:225], v[78:81]
	v_mfma_f32_16x16x32_bf16 v[74:77], v[158:161], v[222:225], v[74:77]
	v_mfma_f32_16x16x32_bf16 v[118:121], v[162:165], v[178:181], v[118:121]
	v_mfma_f32_16x16x32_bf16 v[114:117], v[170:173], v[178:181], v[114:117]
	v_mfma_f32_16x16x32_bf16 v[102:105], v[162:165], v[186:189], v[102:105]
	v_mfma_f32_16x16x32_bf16 v[98:101], v[170:173], v[186:189], v[98:101]
	v_mfma_f32_16x16x32_bf16 v[86:89], v[162:165], v[194:197], v[86:89]
	v_mfma_f32_16x16x32_bf16 v[82:85], v[170:173], v[194:197], v[82:85]
	v_mfma_f32_16x16x32_bf16 v[70:73], v[162:165], v[202:205], v[70:73]
	v_mfma_f32_16x16x32_bf16 v[66:69], v[170:173], v[202:205], v[66:69]
	v_mfma_f32_16x16x32_bf16 v[118:121], v[166:169], v[182:185], v[118:121]
	v_mfma_f32_16x16x32_bf16 v[114:117], v[174:177], v[182:185], v[114:117]
	v_mfma_f32_16x16x32_bf16 v[102:105], v[166:169], v[190:193], v[102:105]
	v_mfma_f32_16x16x32_bf16 v[98:101], v[174:177], v[190:193], v[98:101]
	v_mfma_f32_16x16x32_bf16 v[86:89], v[166:169], v[198:201], v[86:89]
	v_mfma_f32_16x16x32_bf16 v[82:85], v[174:177], v[198:201], v[82:85]
	v_mfma_f32_16x16x32_bf16 v[70:73], v[166:169], v[222:225], v[70:73]
	v_mfma_f32_16x16x32_bf16 v[66:69], v[174:177], v[222:225], v[66:69]
	s_setprio 0
	s_barrier
	s_add_i32 s4, s49, s30
	v_lshl_add_u64 v[142:143], v[142:143], 0, s[44:45]
	s_mov_b32 m0, s4
	ds_read_b128 v[178:181], v144 offset:49152
	ds_read_b128 v[182:185], v144 offset:50176
	ds_read_b128 v[186:189], v144 offset:51200
	ds_read_b128 v[190:193], v144 offset:52224
	ds_read_b128 v[194:197], v144 offset:53248
	ds_read_b128 v[198:201], v144 offset:54272
	ds_read_b128 v[202:205], v144 offset:55296
	ds_read_b128 v[222:225], v144 offset:56320
	global_load_lds_dwordx4 v[142:143], off
	s_add_i32 m0, s4, 0x2000
	s_add_u32 s4, s26, 0x40080
	v_lshl_add_u64 v[142:143], v[206:207], 0, s[44:45]
	s_addc_u32 s5, s27, 0
	s_add_i32 s26, s50, s30
	global_load_lds_dwordx4 v[142:143], off
	v_lshl_add_u64 v[142:143], s[4:5], 0, v[130:131]
	s_mov_b32 m0, s26
	s_nop 0
	global_load_lds_dwordx4 v[142:143], off
	v_lshl_add_u64 v[142:143], s[4:5], 0, v[132:133]
	s_add_i32 m0, s26, 0x2000
	s_nop 0
	global_load_lds_dwordx4 v[142:143], off
	v_lshl_add_u64 v[142:143], v[218:219], 0, s[44:45]
	s_mov_b32 m0, s37
	s_nop 0
	global_load_lds_dwordx4 v[142:143], off
	v_lshl_add_u64 v[142:143], v[226:227], 0, s[44:45]
	s_mov_b32 m0, s38
	s_nop 0
	global_load_lds_dwordx4 v[142:143], off
	s_waitcnt vmcnt(8)
	s_waitcnt lgkmcnt(0)
	s_barrier
	s_setprio 1
	s_waitcnt lgkmcnt(0)
	v_mfma_f32_16x16x32_bf16 v[62:65], v[146:149], v[178:181], v[62:65]
	v_mfma_f32_16x16x32_bf16 v[58:61], v[154:157], v[178:181], v[58:61]
	v_mfma_f32_16x16x32_bf16 v[46:49], v[146:149], v[186:189], v[46:49]
	v_mfma_f32_16x16x32_bf16 v[42:45], v[154:157], v[186:189], v[42:45]
	v_mfma_f32_16x16x32_bf16 v[30:33], v[146:149], v[194:197], v[30:33]
	v_mfma_f32_16x16x32_bf16 v[26:29], v[154:157], v[194:197], v[26:29]
	v_mfma_f32_16x16x32_bf16 v[14:17], v[146:149], v[202:205], v[14:17]
	v_mfma_f32_16x16x32_bf16 v[10:13], v[154:157], v[202:205], v[10:13]
	v_mfma_f32_16x16x32_bf16 v[62:65], v[150:153], v[182:185], v[62:65]
	v_mfma_f32_16x16x32_bf16 v[58:61], v[158:161], v[182:185], v[58:61]
	v_mfma_f32_16x16x32_bf16 v[46:49], v[150:153], v[190:193], v[46:49]
	v_mfma_f32_16x16x32_bf16 v[42:45], v[158:161], v[190:193], v[42:45]
	v_mfma_f32_16x16x32_bf16 v[30:33], v[150:153], v[198:201], v[30:33]
	v_mfma_f32_16x16x32_bf16 v[26:29], v[158:161], v[198:201], v[26:29]
	v_mfma_f32_16x16x32_bf16 v[14:17], v[150:153], v[222:225], v[14:17]
	v_mfma_f32_16x16x32_bf16 v[10:13], v[158:161], v[222:225], v[10:13]
	v_mfma_f32_16x16x32_bf16 v[54:57], v[162:165], v[178:181], v[54:57]
	v_mfma_f32_16x16x32_bf16 v[50:53], v[170:173], v[178:181], v[50:53]
	v_mfma_f32_16x16x32_bf16 v[38:41], v[162:165], v[186:189], v[38:41]
	v_mfma_f32_16x16x32_bf16 v[34:37], v[170:173], v[186:189], v[34:37]
	v_mfma_f32_16x16x32_bf16 v[22:25], v[162:165], v[194:197], v[22:25]
	v_mfma_f32_16x16x32_bf16 v[18:21], v[170:173], v[194:197], v[18:21]
	v_mfma_f32_16x16x32_bf16 v[6:9], v[162:165], v[202:205], v[6:9]
	v_mfma_f32_16x16x32_bf16 v[2:5], v[170:173], v[202:205], v[2:5]
	v_mfma_f32_16x16x32_bf16 v[54:57], v[166:169], v[182:185], v[54:57]
	v_mfma_f32_16x16x32_bf16 v[50:53], v[174:177], v[182:185], v[50:53]
	v_mfma_f32_16x16x32_bf16 v[38:41], v[166:169], v[190:193], v[38:41]
	v_mfma_f32_16x16x32_bf16 v[34:37], v[174:177], v[190:193], v[34:37]
	v_mfma_f32_16x16x32_bf16 v[22:25], v[166:169], v[198:201], v[22:25]
	v_mfma_f32_16x16x32_bf16 v[18:21], v[174:177], v[198:201], v[18:21]
	v_mfma_f32_16x16x32_bf16 v[6:9], v[166:169], v[222:225], v[6:9]
	v_mfma_f32_16x16x32_bf16 v[2:5], v[174:177], v[222:225], v[2:5]
	s_setprio 0
	s_barrier
	s_add_i32 s48, s48, 2
	s_add_u32 s46, s46, 0x100
	s_addc_u32 s47, s47, 0
	s_cmp_gt_u32 s48, 13
	s_mov_b64 s[4:5], s[2:3]
	s_cbranch_scc0 .LBB0_650
	s_and_b64 vcc, exec, s[12:13]
	s_cbranch_vccz .LBB0_653
	s_barrier

.LBB0_783:
	s_add_u32 s2, s4, 0xfffc0080
	s_addc_u32 s3, s5, -1
	s_add_i32 s48, 0, 0x10000
	s_cmp_eq_u32 s47, 12
	s_cselect_b32 s27, s17, s3
	s_cselect_b32 s26, s25, s2
	s_cselect_b32 s3, s15, s46
	s_cselect_b32 s2, s41, s42
	s_add_i32 s50, 0, 0x14000
	v_add_u32_e32 v154, s48, v140
	v_add_u32_e32 v170, s50, v140
	ds_read_b128 v[142:145], v154
	ds_read_b128 v[146:149], v154 offset:1024
	ds_read_b128 v[150:153], v154 offset:2048
	ds_read_b128 v[154:157], v154 offset:3072
	ds_read_b128 v[158:161], v170
	ds_read_b128 v[162:165], v170 offset:1024
	ds_read_b128 v[166:169], v170 offset:2048
	ds_read_b128 v[170:173], v170 offset:3072
	v_lshl_add_u64 v[206:207], s[4:5], 0, v[136:137]
	s_add_i32 m0, s23, 0xc000
	ds_read_b128 v[174:177], v141
	ds_read_b128 v[178:181], v141 offset:1024
	ds_read_b128 v[182:185], v141 offset:2048
	ds_read_b128 v[186:189], v141 offset:3072
	ds_read_b128 v[190:193], v141 offset:4096
	ds_read_b128 v[194:197], v141 offset:5120
	ds_read_b128 v[198:201], v141 offset:6144
	ds_read_b128 v[202:205], v141 offset:7168
	global_load_lds_dwordx4 v[206:207], off
	v_lshl_add_u64 v[206:207], s[4:5], 0, v[138:139]
	s_add_i32 m0, s23, 0xe000
	s_nop 0
	global_load_lds_dwordx4 v[206:207], off
	s_waitcnt vmcnt(8)
	s_waitcnt lgkmcnt(0)
	s_barrier
	s_setprio 1
	s_waitcnt lgkmcnt(0)
	v_mfma_f32_16x16x32_bf16 v[122:125], v[142:145], v[174:177], v[122:125]
	v_mfma_f32_16x16x32_bf16 v[114:117], v[150:153], v[174:177], v[114:117]
	v_mfma_f32_16x16x32_bf16 v[106:109], v[142:145], v[182:185], v[106:109]
	v_mfma_f32_16x16x32_bf16 v[98:101], v[150:153], v[182:185], v[98:101]
	v_mfma_f32_16x16x32_bf16 v[90:93], v[142:145], v[190:193], v[90:93]
	v_mfma_f32_16x16x32_bf16 v[82:85], v[150:153], v[190:193], v[82:85]
	v_mfma_f32_16x16x32_bf16 v[74:77], v[142:145], v[198:201], v[74:77]
	v_mfma_f32_16x16x32_bf16 v[66:69], v[150:153], v[198:201], v[66:69]
	v_mfma_f32_16x16x32_bf16 v[122:125], v[146:149], v[178:181], v[122:125]
	v_mfma_f32_16x16x32_bf16 v[114:117], v[154:157], v[178:181], v[114:117]
	v_mfma_f32_16x16x32_bf16 v[106:109], v[146:149], v[186:189], v[106:109]
	v_mfma_f32_16x16x32_bf16 v[98:101], v[154:157], v[186:189], v[98:101]
	v_mfma_f32_16x16x32_bf16 v[90:93], v[146:149], v[194:197], v[90:93]
	v_mfma_f32_16x16x32_bf16 v[82:85], v[154:157], v[194:197], v[82:85]
	v_mfma_f32_16x16x32_bf16 v[74:77], v[146:149], v[202:205], v[74:77]
	v_mfma_f32_16x16x32_bf16 v[66:69], v[154:157], v[202:205], v[66:69]
	v_mfma_f32_16x16x32_bf16 v[126:129], v[158:161], v[174:177], v[126:129]
	v_mfma_f32_16x16x32_bf16 v[118:121], v[166:169], v[174:177], v[118:121]
	v_mfma_f32_16x16x32_bf16 v[110:113], v[158:161], v[182:185], v[110:113]
	v_mfma_f32_16x16x32_bf16 v[102:105], v[166:169], v[182:185], v[102:105]
	v_mfma_f32_16x16x32_bf16 v[94:97], v[158:161], v[190:193], v[94:97]
	v_mfma_f32_16x16x32_bf16 v[86:89], v[166:169], v[190:193], v[86:89]
	v_mfma_f32_16x16x32_bf16 v[78:81], v[158:161], v[198:201], v[78:81]
	v_mfma_f32_16x16x32_bf16 v[70:73], v[166:169], v[198:201], v[70:73]
	v_mfma_f32_16x16x32_bf16 v[126:129], v[162:165], v[178:181], v[126:129]
	v_mfma_f32_16x16x32_bf16 v[118:121], v[170:173], v[178:181], v[118:121]
	v_mfma_f32_16x16x32_bf16 v[110:113], v[162:165], v[186:189], v[110:113]
	v_mfma_f32_16x16x32_bf16 v[102:105], v[170:173], v[186:189], v[102:105]
	v_mfma_f32_16x16x32_bf16 v[94:97], v[162:165], v[194:197], v[94:97]
	v_mfma_f32_16x16x32_bf16 v[86:89], v[170:173], v[194:197], v[86:89]
	v_mfma_f32_16x16x32_bf16 v[78:81], v[162:165], v[202:205], v[78:81]
	v_mfma_f32_16x16x32_bf16 v[70:73], v[170:173], v[202:205], v[70:73]
	s_setprio 0
	s_barrier
	s_add_i32 s48, s48, s28
	v_lshl_add_u64 v[206:207], s[2:3], 0, v[132:133]
	s_mov_b32 m0, s48
	ds_read_b128 v[174:177], v141 offset:16384
	ds_read_b128 v[178:181], v141 offset:17408
	ds_read_b128 v[182:185], v141 offset:18432
	ds_read_b128 v[186:189], v141 offset:19456
	ds_read_b128 v[190:193], v141 offset:20480
	ds_read_b128 v[194:197], v141 offset:21504
	ds_read_b128 v[198:201], v141 offset:22528
	ds_read_b128 v[202:205], v141 offset:23552
	global_load_lds_dwordx4 v[206:207], off
	s_add_i32 m0, s48, 0x2000
	s_add_u32 s48, s2, 0x40000
	v_lshl_add_u64 v[218:219], s[2:3], 0, v[130:131]
	s_addc_u32 s49, s3, 0
	s_add_i32 s50, s50, s28
	global_load_lds_dwordx4 v[218:219], off
	v_lshl_add_u64 v[222:223], s[48:49], 0, v[132:133]
	s_mov_b32 m0, s50
	v_lshl_add_u64 v[224:225], s[26:27], 0, v[130:131]
	global_load_lds_dwordx4 v[222:223], off
	v_lshl_add_u64 v[222:223], s[48:49], 0, v[130:131]
	s_add_i32 m0, s50, 0x2000
	s_nop 0
	global_load_lds_dwordx4 v[222:223], off
	v_lshl_add_u64 v[222:223], s[26:27], 0, v[132:133]
	s_mov_b32 m0, s23
	s_nop 0
	global_load_lds_dwordx4 v[222:223], off
	s_mov_b32 m0, s31
	s_nop 0
	global_load_lds_dwordx4 v[224:225], off
	s_waitcnt vmcnt(8)
	s_waitcnt lgkmcnt(0)
	s_barrier
	s_setprio 1
	s_waitcnt lgkmcnt(0)
	v_mfma_f32_16x16x32_bf16 v[58:61], v[142:145], v[174:177], v[58:61]
	v_mfma_f32_16x16x32_bf16 v[50:53], v[150:153], v[174:177], v[50:53]
	v_mfma_f32_16x16x32_bf16 v[42:45], v[142:145], v[182:185], v[42:45]
	v_mfma_f32_16x16x32_bf16 v[34:37], v[150:153], v[182:185], v[34:37]
	v_mfma_f32_16x16x32_bf16 v[26:29], v[142:145], v[190:193], v[26:29]
	v_mfma_f32_16x16x32_bf16 v[18:21], v[150:153], v[190:193], v[18:21]
	v_mfma_f32_16x16x32_bf16 v[10:13], v[142:145], v[198:201], v[10:13]
	v_mfma_f32_16x16x32_bf16 v[2:5], v[150:153], v[198:201], v[2:5]
	v_mfma_f32_16x16x32_bf16 v[58:61], v[146:149], v[178:181], v[58:61]
	v_mfma_f32_16x16x32_bf16 v[50:53], v[154:157], v[178:181], v[50:53]
	v_mfma_f32_16x16x32_bf16 v[42:45], v[146:149], v[186:189], v[42:45]
	v_mfma_f32_16x16x32_bf16 v[34:37], v[154:157], v[186:189], v[34:37]
	v_mfma_f32_16x16x32_bf16 v[26:29], v[146:149], v[194:197], v[26:29]
	v_mfma_f32_16x16x32_bf16 v[18:21], v[154:157], v[194:197], v[18:21]
	v_mfma_f32_16x16x32_bf16 v[10:13], v[146:149], v[202:205], v[10:13]
	v_mfma_f32_16x16x32_bf16 v[2:5], v[154:157], v[202:205], v[2:5]
	v_mfma_f32_16x16x32_bf16 v[62:65], v[158:161], v[174:177], v[62:65]
	v_mfma_f32_16x16x32_bf16 v[54:57], v[166:169], v[174:177], v[54:57]
	v_mfma_f32_16x16x32_bf16 v[46:49], v[158:161], v[182:185], v[46:49]
	v_mfma_f32_16x16x32_bf16 v[38:41], v[166:169], v[182:185], v[38:41]
	v_mfma_f32_16x16x32_bf16 v[30:33], v[158:161], v[190:193], v[30:33]
	v_mfma_f32_16x16x32_bf16 v[22:25], v[166:169], v[190:193], v[22:25]
	v_mfma_f32_16x16x32_bf16 v[14:17], v[158:161], v[198:201], v[14:17]
	v_mfma_f32_16x16x32_bf16 v[6:9], v[166:169], v[198:201], v[6:9]
	v_mfma_f32_16x16x32_bf16 v[62:65], v[162:165], v[178:181], v[62:65]
	v_mfma_f32_16x16x32_bf16 v[54:57], v[170:173], v[178:181], v[54:57]
	v_mfma_f32_16x16x32_bf16 v[46:49], v[162:165], v[186:189], v[46:49]
	v_mfma_f32_16x16x32_bf16 v[38:41], v[170:173], v[186:189], v[38:41]
	v_mfma_f32_16x16x32_bf16 v[30:33], v[162:165], v[194:197], v[30:33]
	v_mfma_f32_16x16x32_bf16 v[22:25], v[170:173], v[194:197], v[22:25]
	v_mfma_f32_16x16x32_bf16 v[14:17], v[162:165], v[202:205], v[14:17]
	v_mfma_f32_16x16x32_bf16 v[6:9], v[170:173], v[202:205], v[6:9]
	s_setprio 0
	s_barrier
	s_add_i32 s48, 0, 0x18000
	s_add_i32 s49, 0, 0x1c000
	v_add_u32_e32 v154, s48, v140
	v_add_u32_e32 v170, s49, v140
	ds_read_b128 v[142:145], v154
	ds_read_b128 v[146:149], v154 offset:1024
	ds_read_b128 v[150:153], v154 offset:2048
	ds_read_b128 v[154:157], v154 offset:3072
	ds_read_b128 v[158:161], v170
	ds_read_b128 v[162:165], v170 offset:1024
	ds_read_b128 v[166:169], v170 offset:2048
	ds_read_b128 v[170:173], v170 offset:3072
	s_add_u32 s26, s26, 0x40000
	s_addc_u32 s27, s27, 0
	s_mov_b32 m0, s33
	v_lshl_add_u64 v[226:227], s[26:27], 0, v[132:133]
	ds_read_b128 v[174:177], v141 offset:32768
	ds_read_b128 v[178:181], v141 offset:33792
	ds_read_b128 v[182:185], v141 offset:34816
	ds_read_b128 v[186:189], v141 offset:35840
	ds_read_b128 v[190:193], v141 offset:36864
	ds_read_b128 v[194:197], v141 offset:37888
	ds_read_b128 v[198:201], v141 offset:38912
	ds_read_b128 v[202:205], v141 offset:39936
	global_load_lds_dwordx4 v[226:227], off
	v_lshl_add_u64 v[226:227], s[26:27], 0, v[130:131]
	s_mov_b32 m0, s34
	s_nop 0
	global_load_lds_dwordx4 v[226:227], off
	s_waitcnt vmcnt(8)
	s_waitcnt lgkmcnt(0)
	s_barrier
	s_setprio 1
	s_waitcnt lgkmcnt(0)
	v_mfma_f32_16x16x32_bf16 v[122:125], v[142:145], v[174:177], v[122:125]
	v_mfma_f32_16x16x32_bf16 v[114:117], v[150:153], v[174:177], v[114:117]
	v_mfma_f32_16x16x32_bf16 v[106:109], v[142:145], v[182:185], v[106:109]
	v_mfma_f32_16x16x32_bf16 v[98:101], v[150:153], v[182:185], v[98:101]
	v_mfma_f32_16x16x32_bf16 v[90:93], v[142:145], v[190:193], v[90:93]
	v_mfma_f32_16x16x32_bf16 v[82:85], v[150:153], v[190:193], v[82:85]
	v_mfma_f32_16x16x32_bf16 v[74:77], v[142:145], v[198:201], v[74:77]
	v_mfma_f32_16x16x32_bf16 v[66:69], v[150:153], v[198:201], v[66:69]
	v_mfma_f32_16x16x32_bf16 v[122:125], v[146:149], v[178:181], v[122:125]
	v_mfma_f32_16x16x32_bf16 v[114:117], v[154:157], v[178:181], v[114:117]
	v_mfma_f32_16x16x32_bf16 v[106:109], v[146:149], v[186:189], v[106:109]
	v_mfma_f32_16x16x32_bf16 v[98:101], v[154:157], v[186:189], v[98:101]
	v_mfma_f32_16x16x32_bf16 v[90:93], v[146:149], v[194:197], v[90:93]
	v_mfma_f32_16x16x32_bf16 v[82:85], v[154:157], v[194:197], v[82:85]
	v_mfma_f32_16x16x32_bf16 v[74:77], v[146:149], v[202:205], v[74:77]
	v_mfma_f32_16x16x32_bf16 v[66:69], v[154:157], v[202:205], v[66:69]
	v_mfma_f32_16x16x32_bf16 v[126:129], v[158:161], v[174:177], v[126:129]
	v_mfma_f32_16x16x32_bf16 v[118:121], v[166:169], v[174:177], v[118:121]
	v_mfma_f32_16x16x32_bf16 v[110:113], v[158:161], v[182:185], v[110:113]
	v_mfma_f32_16x16x32_bf16 v[102:105], v[166:169], v[182:185], v[102:105]
	v_mfma_f32_16x16x32_bf16 v[94:97], v[158:161], v[190:193], v[94:97]
	v_mfma_f32_16x16x32_bf16 v[86:89], v[166:169], v[190:193], v[86:89]
	v_mfma_f32_16x16x32_bf16 v[78:81], v[158:161], v[198:201], v[78:81]
	v_mfma_f32_16x16x32_bf16 v[70:73], v[166:169], v[198:201], v[70:73]
	v_mfma_f32_16x16x32_bf16 v[126:129], v[162:165], v[178:181], v[126:129]
	v_mfma_f32_16x16x32_bf16 v[118:121], v[170:173], v[178:181], v[118:121]
	v_mfma_f32_16x16x32_bf16 v[110:113], v[162:165], v[186:189], v[110:113]
	v_mfma_f32_16x16x32_bf16 v[102:105], v[170:173], v[186:189], v[102:105]
	v_mfma_f32_16x16x32_bf16 v[94:97], v[162:165], v[194:197], v[94:97]
	v_mfma_f32_16x16x32_bf16 v[86:89], v[170:173], v[194:197], v[86:89]
	v_mfma_f32_16x16x32_bf16 v[78:81], v[162:165], v[202:205], v[78:81]
	v_mfma_f32_16x16x32_bf16 v[70:73], v[170:173], v[202:205], v[70:73]
	s_setprio 0
	s_barrier
	s_add_i32 s26, s48, s28
	v_lshl_add_u64 v[206:207], v[206:207], 0, s[44:45]
	s_mov_b32 m0, s26
	ds_read_b128 v[174:177], v141 offset:49152
	ds_read_b128 v[178:181], v141 offset:50176
	ds_read_b128 v[182:185], v141 offset:51200
	ds_read_b128 v[186:189], v141 offset:52224
	ds_read_b128 v[190:193], v141 offset:53248
	ds_read_b128 v[194:197], v141 offset:54272
	ds_read_b128 v[198:201], v141 offset:55296
	ds_read_b128 v[202:205], v141 offset:56320
	global_load_lds_dwordx4 v[206:207], off
	s_add_i32 m0, s26, 0x2000
	s_add_u32 s2, s2, 0x40080
	v_lshl_add_u64 v[206:207], v[218:219], 0, s[44:45]
	s_addc_u32 s3, s3, 0
	s_add_i32 s26, s49, s28
	global_load_lds_dwordx4 v[206:207], off
	v_lshl_add_u64 v[206:207], s[2:3], 0, v[132:133]
	s_mov_b32 m0, s26
	s_nop 0
	global_load_lds_dwordx4 v[206:207], off
	v_lshl_add_u64 v[206:207], s[2:3], 0, v[130:131]
	s_add_i32 m0, s26, 0x2000
	s_nop 0
	global_load_lds_dwordx4 v[206:207], off
	v_lshl_add_u64 v[206:207], v[222:223], 0, s[44:45]
	s_mov_b32 m0, s35
	s_nop 0
	global_load_lds_dwordx4 v[206:207], off
	v_lshl_add_u64 v[206:207], v[224:225], 0, s[44:45]
	s_mov_b32 m0, s36
	s_nop 0
	global_load_lds_dwordx4 v[206:207], off
	s_waitcnt vmcnt(8)
	s_waitcnt lgkmcnt(0)
	s_barrier
	s_setprio 1
	s_waitcnt lgkmcnt(0)
	v_mfma_f32_16x16x32_bf16 v[58:61], v[142:145], v[174:177], v[58:61]
	v_mfma_f32_16x16x32_bf16 v[50:53], v[150:153], v[174:177], v[50:53]
	v_mfma_f32_16x16x32_bf16 v[42:45], v[142:145], v[182:185], v[42:45]
	v_mfma_f32_16x16x32_bf16 v[34:37], v[150:153], v[182:185], v[34:37]
	v_mfma_f32_16x16x32_bf16 v[26:29], v[142:145], v[190:193], v[26:29]
	v_mfma_f32_16x16x32_bf16 v[18:21], v[150:153], v[190:193], v[18:21]
	v_mfma_f32_16x16x32_bf16 v[10:13], v[142:145], v[198:201], v[10:13]
	v_mfma_f32_16x16x32_bf16 v[2:5], v[150:153], v[198:201], v[2:5]
	v_mfma_f32_16x16x32_bf16 v[58:61], v[146:149], v[178:181], v[58:61]
	v_mfma_f32_16x16x32_bf16 v[50:53], v[154:157], v[178:181], v[50:53]
	v_mfma_f32_16x16x32_bf16 v[42:45], v[146:149], v[186:189], v[42:45]
	v_mfma_f32_16x16x32_bf16 v[34:37], v[154:157], v[186:189], v[34:37]
	v_mfma_f32_16x16x32_bf16 v[26:29], v[146:149], v[194:197], v[26:29]
	v_mfma_f32_16x16x32_bf16 v[18:21], v[154:157], v[194:197], v[18:21]
	v_mfma_f32_16x16x32_bf16 v[10:13], v[146:149], v[202:205], v[10:13]
	v_mfma_f32_16x16x32_bf16 v[2:5], v[154:157], v[202:205], v[2:5]
	v_mfma_f32_16x16x32_bf16 v[62:65], v[158:161], v[174:177], v[62:65]
	v_mfma_f32_16x16x32_bf16 v[54:57], v[166:169], v[174:177], v[54:57]
	v_mfma_f32_16x16x32_bf16 v[46:49], v[158:161], v[182:185], v[46:49]
	v_mfma_f32_16x16x32_bf16 v[38:41], v[166:169], v[182:185], v[38:41]
	v_mfma_f32_16x16x32_bf16 v[30:33], v[158:161], v[190:193], v[30:33]
	v_mfma_f32_16x16x32_bf16 v[22:25], v[166:169], v[190:193], v[22:25]
	v_mfma_f32_16x16x32_bf16 v[14:17], v[158:161], v[198:201], v[14:17]
	v_mfma_f32_16x16x32_bf16 v[6:9], v[166:169], v[198:201], v[6:9]
	v_mfma_f32_16x16x32_bf16 v[62:65], v[162:165], v[178:181], v[62:65]
	v_mfma_f32_16x16x32_bf16 v[54:57], v[170:173], v[178:181], v[54:57]
	v_mfma_f32_16x16x32_bf16 v[46:49], v[162:165], v[186:189], v[46:49]
	v_mfma_f32_16x16x32_bf16 v[38:41], v[170:173], v[186:189], v[38:41]
	v_mfma_f32_16x16x32_bf16 v[30:33], v[162:165], v[194:197], v[30:33]
	v_mfma_f32_16x16x32_bf16 v[22:25], v[170:173], v[194:197], v[22:25]
	v_mfma_f32_16x16x32_bf16 v[14:17], v[162:165], v[202:205], v[14:17]
	v_mfma_f32_16x16x32_bf16 v[6:9], v[170:173], v[202:205], v[6:9]
	s_setprio 0
	s_barrier
	s_add_i32 s47, s47, 2
	s_add_u32 s4, s4, 0x100
	s_addc_u32 s5, s5, 0
	s_add_u32 s42, s42, 0x100
	s_addc_u32 s46, s46, 0
	s_cmp_gt_u32 s47, 13
	s_cbranch_scc0 .LBB0_783
	s_and_b64 vcc, exec, s[12:13]
	s_cbranch_vccz .LBB0_786
	s_barrier

.LBB0_849:
	s_add_u32 s2, s18, 0x100
	s_addc_u32 s3, s19, 0
	s_add_i32 s47, 0, 0x10000
	s_cmp_eq_u32 s46, 40
	s_cselect_b32 s23, s9, s3
	s_cselect_b32 s22, s8, s2
	v_add_u32_e32 v0, s47, v135
	s_cselect_b32 s21, s15, s42
	s_cselect_b32 s20, s14, s17
	s_add_i32 s48, 0, 0x14000
	ds_read_b128 v[146:149], v0
	ds_read_b128 v[150:153], v0 offset:1024
	ds_read_b128 v[154:157], v0 offset:2048
	ds_read_b128 v[158:161], v0 offset:3072
	v_add_u32_e32 v0, s48, v135
	ds_read_b128 v[162:165], v0
	ds_read_b128 v[166:169], v0 offset:1024
	ds_read_b128 v[170:173], v0 offset:2048
	ds_read_b128 v[174:177], v0 offset:3072
	v_lshl_add_u64 v[142:143], s[18:19], 0, v[138:139]
	s_add_i32 m0, s25, 0xc000
	ds_read_b128 v[178:181], v144
	ds_read_b128 v[182:185], v144 offset:1024
	ds_read_b128 v[186:189], v144 offset:2048
	ds_read_b128 v[190:193], v144 offset:3072
	ds_read_b128 v[194:197], v144 offset:4096
	ds_read_b128 v[198:201], v144 offset:5120
	ds_read_b128 v[202:205], v144 offset:6144
	ds_read_b128 v[222:225], v144 offset:7168
	global_load_lds_dwordx4 v[142:143], off
	v_lshl_add_u64 v[142:143], s[18:19], 0, v[140:141]
	s_add_i32 m0, s25, 0xe000
	s_nop 0
	global_load_lds_dwordx4 v[142:143], off
	s_waitcnt vmcnt(8)
	s_waitcnt lgkmcnt(0)
	s_barrier
	s_setprio 1
	s_waitcnt lgkmcnt(0)
	v_mfma_f32_16x16x32_bf16 v[126:129], v[146:149], v[178:181], v[126:129]
	v_mfma_f32_16x16x32_bf16 v[122:125], v[154:157], v[178:181], v[122:125]
	v_mfma_f32_16x16x32_bf16 v[110:113], v[146:149], v[186:189], v[110:113]
	v_mfma_f32_16x16x32_bf16 v[106:109], v[154:157], v[186:189], v[106:109]
	v_mfma_f32_16x16x32_bf16 v[94:97], v[146:149], v[194:197], v[94:97]
	v_mfma_f32_16x16x32_bf16 v[90:93], v[154:157], v[194:197], v[90:93]
	v_mfma_f32_16x16x32_bf16 v[78:81], v[146:149], v[202:205], v[78:81]
	v_mfma_f32_16x16x32_bf16 v[74:77], v[154:157], v[202:205], v[74:77]
	v_mfma_f32_16x16x32_bf16 v[126:129], v[150:153], v[182:185], v[126:129]
	v_mfma_f32_16x16x32_bf16 v[122:125], v[158:161], v[182:185], v[122:125]
	v_mfma_f32_16x16x32_bf16 v[110:113], v[150:153], v[190:193], v[110:113]
	v_mfma_f32_16x16x32_bf16 v[106:109], v[158:161], v[190:193], v[106:109]
	v_mfma_f32_16x16x32_bf16 v[94:97], v[150:153], v[198:201], v[94:97]
	v_mfma_f32_16x16x32_bf16 v[90:93], v[158:161], v[198:201], v[90:93]
	v_mfma_f32_16x16x32_bf16 v[78:81], v[150:153], v[222:225], v[78:81]
	v_mfma_f32_16x16x32_bf16 v[74:77], v[158:161], v[222:225], v[74:77]
	v_mfma_f32_16x16x32_bf16 v[118:121], v[162:165], v[178:181], v[118:121]
	v_mfma_f32_16x16x32_bf16 v[114:117], v[170:173], v[178:181], v[114:117]
	v_mfma_f32_16x16x32_bf16 v[102:105], v[162:165], v[186:189], v[102:105]
	v_mfma_f32_16x16x32_bf16 v[98:101], v[170:173], v[186:189], v[98:101]
	v_mfma_f32_16x16x32_bf16 v[86:89], v[162:165], v[194:197], v[86:89]
	v_mfma_f32_16x16x32_bf16 v[82:85], v[170:173], v[194:197], v[82:85]
	v_mfma_f32_16x16x32_bf16 v[70:73], v[162:165], v[202:205], v[70:73]
	v_mfma_f32_16x16x32_bf16 v[66:69], v[170:173], v[202:205], v[66:69]
	v_mfma_f32_16x16x32_bf16 v[118:121], v[166:169], v[182:185], v[118:121]
	v_mfma_f32_16x16x32_bf16 v[114:117], v[174:177], v[182:185], v[114:117]
	v_mfma_f32_16x16x32_bf16 v[102:105], v[166:169], v[190:193], v[102:105]
	v_mfma_f32_16x16x32_bf16 v[98:101], v[174:177], v[190:193], v[98:101]
	v_mfma_f32_16x16x32_bf16 v[86:89], v[166:169], v[198:201], v[86:89]
	v_mfma_f32_16x16x32_bf16 v[82:85], v[174:177], v[198:201], v[82:85]
	v_mfma_f32_16x16x32_bf16 v[70:73], v[166:169], v[222:225], v[70:73]
	v_mfma_f32_16x16x32_bf16 v[66:69], v[174:177], v[222:225], v[66:69]
	s_setprio 0
	s_barrier
	s_add_i32 s18, s47, s24
	v_lshl_add_u64 v[142:143], s[20:21], 0, v[130:131]
	s_mov_b32 m0, s18
	ds_read_b128 v[178:181], v144 offset:16384
	ds_read_b128 v[182:185], v144 offset:17408
	ds_read_b128 v[186:189], v144 offset:18432
	ds_read_b128 v[190:193], v144 offset:19456
	ds_read_b128 v[194:197], v144 offset:20480
	ds_read_b128 v[198:201], v144 offset:21504
	ds_read_b128 v[202:205], v144 offset:22528
	ds_read_b128 v[222:225], v144 offset:23552
	global_load_lds_dwordx4 v[142:143], off
	s_add_i32 m0, s18, 0x2000
	s_add_u32 s18, s20, 0xb0000
	v_lshl_add_u64 v[206:207], s[20:21], 0, v[132:133]
	s_addc_u32 s19, s21, 0
	s_add_i32 s47, s48, s24
	global_load_lds_dwordx4 v[206:207], off
	v_lshl_add_u64 v[218:219], s[18:19], 0, v[130:131]
	s_mov_b32 m0, s47
	v_lshl_add_u64 v[226:227], s[22:23], 0, v[132:133]
	global_load_lds_dwordx4 v[218:219], off
	v_lshl_add_u64 v[218:219], s[18:19], 0, v[132:133]
	s_add_i32 m0, s47, 0x2000
	s_nop 0
	global_load_lds_dwordx4 v[218:219], off
	v_lshl_add_u64 v[218:219], s[22:23], 0, v[130:131]
	s_mov_b32 m0, s25
	s_nop 0
	global_load_lds_dwordx4 v[218:219], off
	s_mov_b32 m0, s26
	s_nop 0
	global_load_lds_dwordx4 v[226:227], off
	s_waitcnt vmcnt(8)
	s_waitcnt lgkmcnt(0)
	s_barrier
	s_setprio 1
	s_waitcnt lgkmcnt(0)
	v_mfma_f32_16x16x32_bf16 v[62:65], v[146:149], v[178:181], v[62:65]
	v_mfma_f32_16x16x32_bf16 v[58:61], v[154:157], v[178:181], v[58:61]
	v_mfma_f32_16x16x32_bf16 v[46:49], v[146:149], v[186:189], v[46:49]
	v_mfma_f32_16x16x32_bf16 v[42:45], v[154:157], v[186:189], v[42:45]
	v_mfma_f32_16x16x32_bf16 v[30:33], v[146:149], v[194:197], v[30:33]
	v_mfma_f32_16x16x32_bf16 v[26:29], v[154:157], v[194:197], v[26:29]
	v_mfma_f32_16x16x32_bf16 v[14:17], v[146:149], v[202:205], v[14:17]
	v_mfma_f32_16x16x32_bf16 v[10:13], v[154:157], v[202:205], v[10:13]
	v_mfma_f32_16x16x32_bf16 v[62:65], v[150:153], v[182:185], v[62:65]
	v_mfma_f32_16x16x32_bf16 v[58:61], v[158:161], v[182:185], v[58:61]
	v_mfma_f32_16x16x32_bf16 v[46:49], v[150:153], v[190:193], v[46:49]
	v_mfma_f32_16x16x32_bf16 v[42:45], v[158:161], v[190:193], v[42:45]
	v_mfma_f32_16x16x32_bf16 v[30:33], v[150:153], v[198:201], v[30:33]
	v_mfma_f32_16x16x32_bf16 v[26:29], v[158:161], v[198:201], v[26:29]
	v_mfma_f32_16x16x32_bf16 v[14:17], v[150:153], v[222:225], v[14:17]
	v_mfma_f32_16x16x32_bf16 v[10:13], v[158:161], v[222:225], v[10:13]
	v_mfma_f32_16x16x32_bf16 v[54:57], v[162:165], v[178:181], v[54:57]
	v_mfma_f32_16x16x32_bf16 v[50:53], v[170:173], v[178:181], v[50:53]
	v_mfma_f32_16x16x32_bf16 v[38:41], v[162:165], v[186:189], v[38:41]
	v_mfma_f32_16x16x32_bf16 v[34:37], v[170:173], v[186:189], v[34:37]
	v_mfma_f32_16x16x32_bf16 v[22:25], v[162:165], v[194:197], v[22:25]
	v_mfma_f32_16x16x32_bf16 v[18:21], v[170:173], v[194:197], v[18:21]
	v_mfma_f32_16x16x32_bf16 v[6:9], v[162:165], v[202:205], v[6:9]
	v_mfma_f32_16x16x32_bf16 v[2:5], v[170:173], v[202:205], v[2:5]
	v_mfma_f32_16x16x32_bf16 v[54:57], v[166:169], v[182:185], v[54:57]
	v_mfma_f32_16x16x32_bf16 v[50:53], v[174:177], v[182:185], v[50:53]
	v_mfma_f32_16x16x32_bf16 v[38:41], v[166:169], v[190:193], v[38:41]
	v_mfma_f32_16x16x32_bf16 v[34:37], v[174:177], v[190:193], v[34:37]
	v_mfma_f32_16x16x32_bf16 v[22:25], v[166:169], v[198:201], v[22:25]
	v_mfma_f32_16x16x32_bf16 v[18:21], v[174:177], v[198:201], v[18:21]
	v_mfma_f32_16x16x32_bf16 v[6:9], v[166:169], v[222:225], v[6:9]
	v_mfma_f32_16x16x32_bf16 v[2:5], v[174:177], v[222:225], v[2:5]
	s_setprio 0
	s_barrier
	s_add_i32 s47, 0, 0x18000
	v_add_u32_e32 v0, s47, v135
	s_add_i32 s48, 0, 0x1c000
	ds_read_b128 v[146:149], v0
	ds_read_b128 v[150:153], v0 offset:1024
	ds_read_b128 v[154:157], v0 offset:2048
	ds_read_b128 v[158:161], v0 offset:3072
	v_add_u32_e32 v0, s48, v135
	ds_read_b128 v[162:165], v0
	ds_read_b128 v[166:169], v0 offset:1024
	ds_read_b128 v[170:173], v0 offset:2048
	ds_read_b128 v[174:177], v0 offset:3072
	s_add_u32 s18, s22, 0xb0000
	s_addc_u32 s19, s23, 0
	s_mov_b32 m0, s27
	v_lshl_add_u64 v[228:229], s[18:19], 0, v[130:131]
	ds_read_b128 v[178:181], v144 offset:32768
	ds_read_b128 v[182:185], v144 offset:33792
	ds_read_b128 v[186:189], v144 offset:34816
	ds_read_b128 v[190:193], v144 offset:35840
	ds_read_b128 v[194:197], v144 offset:36864
	ds_read_b128 v[198:201], v144 offset:37888
	ds_read_b128 v[202:205], v144 offset:38912
	ds_read_b128 v[222:225], v144 offset:39936
	global_load_lds_dwordx4 v[228:229], off
	v_lshl_add_u64 v[228:229], s[18:19], 0, v[132:133]
	s_mov_b32 m0, s28
	s_nop 0
	global_load_lds_dwordx4 v[228:229], off
	s_waitcnt vmcnt(8)
	s_waitcnt lgkmcnt(0)
	s_barrier
	s_setprio 1
	s_waitcnt lgkmcnt(0)
	v_mfma_f32_16x16x32_bf16 v[126:129], v[146:149], v[178:181], v[126:129]
	v_mfma_f32_16x16x32_bf16 v[122:125], v[154:157], v[178:181], v[122:125]
	v_mfma_f32_16x16x32_bf16 v[110:113], v[146:149], v[186:189], v[110:113]
	v_mfma_f32_16x16x32_bf16 v[106:109], v[154:157], v[186:189], v[106:109]
	v_mfma_f32_16x16x32_bf16 v[94:97], v[146:149], v[194:197], v[94:97]
	v_mfma_f32_16x16x32_bf16 v[90:93], v[154:157], v[194:197], v[90:93]
	v_mfma_f32_16x16x32_bf16 v[78:81], v[146:149], v[202:205], v[78:81]
	v_mfma_f32_16x16x32_bf16 v[74:77], v[154:157], v[202:205], v[74:77]
	v_mfma_f32_16x16x32_bf16 v[126:129], v[150:153], v[182:185], v[126:129]
	v_mfma_f32_16x16x32_bf16 v[122:125], v[158:161], v[182:185], v[122:125]
	v_mfma_f32_16x16x32_bf16 v[110:113], v[150:153], v[190:193], v[110:113]
	v_mfma_f32_16x16x32_bf16 v[106:109], v[158:161], v[190:193], v[106:109]
	v_mfma_f32_16x16x32_bf16 v[94:97], v[150:153], v[198:201], v[94:97]
	v_mfma_f32_16x16x32_bf16 v[90:93], v[158:161], v[198:201], v[90:93]
	v_mfma_f32_16x16x32_bf16 v[78:81], v[150:153], v[222:225], v[78:81]
	v_mfma_f32_16x16x32_bf16 v[74:77], v[158:161], v[222:225], v[74:77]
	v_mfma_f32_16x16x32_bf16 v[118:121], v[162:165], v[178:181], v[118:121]
	v_mfma_f32_16x16x32_bf16 v[114:117], v[170:173], v[178:181], v[114:117]
	v_mfma_f32_16x16x32_bf16 v[102:105], v[162:165], v[186:189], v[102:105]
	v_mfma_f32_16x16x32_bf16 v[98:101], v[170:173], v[186:189], v[98:101]
	v_mfma_f32_16x16x32_bf16 v[86:89], v[162:165], v[194:197], v[86:89]
	v_mfma_f32_16x16x32_bf16 v[82:85], v[170:173], v[194:197], v[82:85]
	v_mfma_f32_16x16x32_bf16 v[70:73], v[162:165], v[202:205], v[70:73]
	v_mfma_f32_16x16x32_bf16 v[66:69], v[170:173], v[202:205], v[66:69]
	v_mfma_f32_16x16x32_bf16 v[118:121], v[166:169], v[182:185], v[118:121]
	v_mfma_f32_16x16x32_bf16 v[114:117], v[174:177], v[182:185], v[114:117]
	v_mfma_f32_16x16x32_bf16 v[102:105], v[166:169], v[190:193], v[102:105]
	v_mfma_f32_16x16x32_bf16 v[98:101], v[174:177], v[190:193], v[98:101]
	v_mfma_f32_16x16x32_bf16 v[86:89], v[166:169], v[198:201], v[86:89]
	v_mfma_f32_16x16x32_bf16 v[82:85], v[174:177], v[198:201], v[82:85]
	v_mfma_f32_16x16x32_bf16 v[70:73], v[166:169], v[222:225], v[70:73]
	v_mfma_f32_16x16x32_bf16 v[66:69], v[174:177], v[222:225], v[66:69]
	s_setprio 0
	s_barrier
	s_add_i32 s18, s47, s24
	v_lshl_add_u64 v[142:143], v[142:143], 0, s[44:45]
	s_mov_b32 m0, s18
	ds_read_b128 v[178:181], v144 offset:49152
	ds_read_b128 v[182:185], v144 offset:50176
	ds_read_b128 v[186:189], v144 offset:51200
	ds_read_b128 v[190:193], v144 offset:52224
	ds_read_b128 v[194:197], v144 offset:53248
	ds_read_b128 v[198:201], v144 offset:54272
	ds_read_b128 v[202:205], v144 offset:55296
	ds_read_b128 v[222:225], v144 offset:56320
	global_load_lds_dwordx4 v[142:143], off
	s_add_i32 m0, s18, 0x2000
	s_add_u32 s18, s20, 0xb0080
	v_lshl_add_u64 v[142:143], v[206:207], 0, s[44:45]
	s_addc_u32 s19, s21, 0
	s_add_i32 s20, s48, s24
	global_load_lds_dwordx4 v[142:143], off
	v_lshl_add_u64 v[142:143], s[18:19], 0, v[130:131]
	s_mov_b32 m0, s20
	s_nop 0
	global_load_lds_dwordx4 v[142:143], off
	v_lshl_add_u64 v[142:143], s[18:19], 0, v[132:133]
	s_add_i32 m0, s20, 0x2000
	s_nop 0
	global_load_lds_dwordx4 v[142:143], off
	v_lshl_add_u64 v[142:143], v[218:219], 0, s[44:45]
	s_mov_b32 m0, s31
	s_nop 0
	global_load_lds_dwordx4 v[142:143], off
	v_lshl_add_u64 v[142:143], v[226:227], 0, s[44:45]
	s_mov_b32 m0, s33
	s_nop 0
	global_load_lds_dwordx4 v[142:143], off
	s_waitcnt vmcnt(8)
	s_waitcnt lgkmcnt(0)
	s_barrier
	s_setprio 1
	s_waitcnt lgkmcnt(0)
	v_mfma_f32_16x16x32_bf16 v[62:65], v[146:149], v[178:181], v[62:65]
	v_mfma_f32_16x16x32_bf16 v[58:61], v[154:157], v[178:181], v[58:61]
	v_mfma_f32_16x16x32_bf16 v[46:49], v[146:149], v[186:189], v[46:49]
	v_mfma_f32_16x16x32_bf16 v[42:45], v[154:157], v[186:189], v[42:45]
	v_mfma_f32_16x16x32_bf16 v[30:33], v[146:149], v[194:197], v[30:33]
	v_mfma_f32_16x16x32_bf16 v[26:29], v[154:157], v[194:197], v[26:29]
	v_mfma_f32_16x16x32_bf16 v[14:17], v[146:149], v[202:205], v[14:17]
	v_mfma_f32_16x16x32_bf16 v[10:13], v[154:157], v[202:205], v[10:13]
	v_mfma_f32_16x16x32_bf16 v[62:65], v[150:153], v[182:185], v[62:65]
	v_mfma_f32_16x16x32_bf16 v[58:61], v[158:161], v[182:185], v[58:61]
	v_mfma_f32_16x16x32_bf16 v[46:49], v[150:153], v[190:193], v[46:49]
	v_mfma_f32_16x16x32_bf16 v[42:45], v[158:161], v[190:193], v[42:45]
	v_mfma_f32_16x16x32_bf16 v[30:33], v[150:153], v[198:201], v[30:33]
	v_mfma_f32_16x16x32_bf16 v[26:29], v[158:161], v[198:201], v[26:29]
	v_mfma_f32_16x16x32_bf16 v[14:17], v[150:153], v[222:225], v[14:17]
	v_mfma_f32_16x16x32_bf16 v[10:13], v[158:161], v[222:225], v[10:13]
	v_mfma_f32_16x16x32_bf16 v[54:57], v[162:165], v[178:181], v[54:57]
	v_mfma_f32_16x16x32_bf16 v[50:53], v[170:173], v[178:181], v[50:53]
	v_mfma_f32_16x16x32_bf16 v[38:41], v[162:165], v[186:189], v[38:41]
	v_mfma_f32_16x16x32_bf16 v[34:37], v[170:173], v[186:189], v[34:37]
	v_mfma_f32_16x16x32_bf16 v[22:25], v[162:165], v[194:197], v[22:25]
	v_mfma_f32_16x16x32_bf16 v[18:21], v[170:173], v[194:197], v[18:21]
	v_mfma_f32_16x16x32_bf16 v[6:9], v[162:165], v[202:205], v[6:9]
	v_mfma_f32_16x16x32_bf16 v[2:5], v[170:173], v[202:205], v[2:5]
	v_mfma_f32_16x16x32_bf16 v[54:57], v[166:169], v[182:185], v[54:57]
	v_mfma_f32_16x16x32_bf16 v[50:53], v[174:177], v[182:185], v[50:53]
	v_mfma_f32_16x16x32_bf16 v[38:41], v[166:169], v[190:193], v[38:41]
	v_mfma_f32_16x16x32_bf16 v[34:37], v[174:177], v[190:193], v[34:37]
	v_mfma_f32_16x16x32_bf16 v[22:25], v[166:169], v[198:201], v[22:25]
	v_mfma_f32_16x16x32_bf16 v[18:21], v[174:177], v[198:201], v[18:21]
	v_mfma_f32_16x16x32_bf16 v[6:9], v[166:169], v[222:225], v[6:9]
	v_mfma_f32_16x16x32_bf16 v[2:5], v[174:177], v[222:225], v[2:5]
	s_setprio 0
	s_barrier
	s_add_i32 s46, s46, 2
	s_add_u32 s17, s17, 0x100
	s_addc_u32 s42, s42, 0
	s_cmp_gt_u32 s46, 41
	s_mov_b64 s[18:19], s[2:3]
	s_cbranch_scc0 .LBB0_849
	s_and_b64 vcc, exec, s[12:13]
	s_cbranch_vccz .LBB0_852
	s_barrier
